# GLA chain step: intra-quad 4x4 transpose then 8-byte stores of the inter-chunk output instead of 32 two-byte stores per lane
# baseline (speedup 1.0000x reference)
.LBB0_493:
	v_lshlrev_b32_e32 v0, 3, v215
	v_mul_lo_u32 v15, v14, s64
	v_add3_u32 v15, 0, v0, v15
	v_cvt_pk_bf16_f32 v96, v16, v17
	v_cvt_pk_bf16_f32 v97, v18, v19
	v_cvt_pk_bf16_f32 v98, v20, v21
	v_cvt_pk_bf16_f32 v99, v22, v23
	ds_read2_b64 v[80:83], v15 offset1:2
	ds_read2_b64 v[238:241], v15 offset0:4 offset1:6
	v_add_u32_e32 v196, 0x2000, v15
	s_waitcnt lgkmcnt(0)
	v_mfma_f32_32x32x16_bf16 v[80:95], v[96:99], v[80:83], 0
	ds_read2_b64 v[100:103], v196 offset0:64 offset1:66
	v_cvt_pk_bf16_f32 v242, v24, v25
	v_cvt_pk_bf16_f32 v243, v26, v27
	v_cvt_pk_bf16_f32 v244, v28, v29
	v_cvt_pk_bf16_f32 v245, v30, v31
	v_cvt_pk_bf16_f32 v112, v32, v33
	v_cvt_pk_bf16_f32 v113, v34, v35
	v_cvt_pk_bf16_f32 v114, v36, v37
	v_cvt_pk_bf16_f32 v115, v38, v39
	s_waitcnt lgkmcnt(0)
	v_mfma_f32_32x32x16_bf16 v[96:111], v[96:99], v[100:103], 0
	ds_read2_b64 v[116:119], v15 offset0:8 offset1:10
	v_cvt_pk_bf16_f32 v246, v40, v41
	v_cvt_pk_bf16_f32 v247, v42, v43
	v_cvt_pk_bf16_f32 v248, v44, v45
	v_cvt_pk_bf16_f32 v249, v46, v47
	s_add_i32 s4, s79, -2
	s_add_i32 s5, s78, 2
	v_mfma_f32_32x32x16_bf16 v[80:95], v[242:245], v[238:241], v[80:95]
	ds_read2_b64 v[238:241], v196 offset0:68 offset1:70
	s_and_b64 s[0:1], s[34:35], exec
	s_cselect_b32 s0, s4, s5
	s_lshl_b32 s0, s0, 6
	s_add_i32 s38, s0, s44
	s_ashr_i32 s39, s38, 31
	s_add_i32 s78, s78, -2
	s_waitcnt lgkmcnt(0)
	v_mfma_f32_32x32x16_bf16 v[128:143], v[112:115], v[116:119], 0
	ds_read2_b64 v[116:119], v196 offset0:72 offset1:74
	s_add_i32 s79, s79, 2
	s_cmp_ge_u32 s80, s43
	v_mfma_f32_32x32x16_bf16 v[96:111], v[242:245], v[238:241], v[96:111]
	ds_read2_b64 v[238:241], v15 offset0:12 offset1:14
	v_cvt_pk_bf16_f32 v242, v64, v65
	v_cvt_pk_bf16_f32 v243, v66, v67
	v_cvt_pk_bf16_f32 v244, v68, v69
	v_cvt_pk_bf16_f32 v245, v70, v71
	s_waitcnt lgkmcnt(0)
	v_mfma_f32_32x32x16_bf16 v[112:127], v[112:115], v[116:119], 0
	v_mfma_f32_32x32x16_bf16 v[128:143], v[246:249], v[238:241], v[128:143]
	ds_read2_b64 v[238:241], v196 offset0:76 offset1:78
	s_waitcnt lgkmcnt(0)
	v_mfma_f32_32x32x16_bf16 v[112:127], v[246:249], v[238:241], v[112:127]
	v_cvt_pk_bf16_f32 v238, v48, v49
	v_cvt_pk_bf16_f32 v239, v50, v51
	v_cvt_pk_bf16_f32 v240, v52, v53
	v_cvt_pk_bf16_f32 v241, v54, v55
	ds_read2_b64 v[246:249], v15 offset0:16 offset1:18
	s_waitcnt lgkmcnt(0)
	v_mfma_f32_32x32x16_bf16 v[80:95], v[238:241], v[246:249], v[80:95]
	ds_read2_b64 v[246:249], v196 offset0:80 offset1:82
	s_waitcnt lgkmcnt(0)
	v_mfma_f32_32x32x16_bf16 v[96:111], v[238:241], v[246:249], v[96:111]
	ds_read2_b64 v[238:241], v15 offset0:24 offset1:26
	ds_read2_b64 v[246:249], v15 offset0:20 offset1:22
	s_waitcnt lgkmcnt(0)
	v_mfma_f32_32x32x16_bf16 v[128:143], v[242:245], v[238:241], v[128:143]
	ds_read2_b64 v[238:241], v196 offset0:88 offset1:90
	s_waitcnt lgkmcnt(0)
	v_mfma_f32_32x32x16_bf16 v[112:127], v[242:245], v[238:241], v[112:127]
	v_cvt_pk_bf16_f32 v238, v56, v57
	v_cvt_pk_bf16_f32 v239, v58, v59
	v_cvt_pk_bf16_f32 v240, v60, v61
	v_cvt_pk_bf16_f32 v241, v62, v63
	v_cvt_pk_bf16_f32 v242, v72, v73
	v_cvt_pk_bf16_f32 v243, v74, v75
	v_cvt_pk_bf16_f32 v244, v76, v77
	v_mfma_f32_32x32x16_bf16 v[80:95], v[238:241], v[246:249], v[80:95]
	ds_read2_b64 v[246:249], v196 offset0:84 offset1:86
	v_cvt_pk_bf16_f32 v245, v78, v79
	s_waitcnt lgkmcnt(0)
	v_mfma_f32_32x32x16_bf16 v[96:111], v[238:241], v[246:249], v[96:111]
	ds_read2_b64 v[238:241], v15 offset0:28 offset1:30
	v_ashrrev_i32_e32 v15, 31, v14
	s_waitcnt lgkmcnt(0)
	v_mfma_f32_32x32x16_bf16 v[128:143], v[242:245], v[238:241], v[128:143]
	ds_read2_b64 v[238:241], v196 offset0:92 offset1:94
	v_lshl_add_u32 v196, v215, 2, s71
	v_ashrrev_i32_e32 v197, 31, v196
	v_lshlrev_b64 v[196:197], 15, v[196:197]
	v_lshl_add_u64 v[196:197], s[68:69], 0, v[196:197]
	v_lshl_add_u64 v[196:197], s[38:39], 1, v[196:197]
	v_lshl_add_u64 v[196:197], v[14:15], 1, v[196:197]
	s_waitcnt lgkmcnt(0)
	v_mfma_f32_32x32x16_bf16 v[112:127], v[242:245], v[238:241], v[112:127]
	s_nop 7
	s_nop 3
	v_add_f32_e32 v80, v80, v128
	v_add_f32_e32 v81, v81, v129
	v_add_f32_e32 v82, v82, v130
	v_add_f32_e32 v83, v83, v131
	v_add_f32_e32 v84, v84, v132
	v_add_f32_e32 v85, v85, v133
	v_add_f32_e32 v86, v86, v134
	v_add_f32_e32 v87, v87, v135
	v_add_f32_e32 v88, v88, v136
	v_add_f32_e32 v89, v89, v137
	v_add_f32_e32 v90, v90, v138
	v_add_f32_e32 v91, v91, v139
	v_add_f32_e32 v92, v92, v140
	v_add_f32_e32 v93, v93, v141
	v_add_f32_e32 v94, v94, v142
	v_add_f32_e32 v95, v95, v143
	v_add_f32_e32 v96, v96, v112
	v_add_f32_e32 v97, v97, v113
	v_add_f32_e32 v98, v98, v114
	v_add_f32_e32 v99, v99, v115
	v_add_f32_e32 v100, v100, v116
	v_add_f32_e32 v101, v101, v117
	v_add_f32_e32 v102, v102, v118
	v_add_f32_e32 v103, v103, v119
	v_add_f32_e32 v104, v104, v120
	v_add_f32_e32 v105, v105, v121
	v_add_f32_e32 v106, v106, v122
	v_add_f32_e32 v107, v107, v123
	v_add_f32_e32 v108, v108, v124
	v_add_f32_e32 v109, v109, v125
	v_add_f32_e32 v110, v110, v126
	v_add_f32_e32 v111, v111, v127
	v_and_b32_e32 v15, 3, v235
	v_mul_u32_u24_e32 v15, 0x7ffe, v15
	v_add_co_u32_e32 v196, vcc, v196, v15
	s_nop 1
	v_addc_co_u32_e32 v197, vcc, 0, v197, vcc
	v_and_b32_e32 v15, 1, v235
	v_cmp_eq_u32_e32 vcc, 0, v15
	s_nop 1
	v_cndmask_b32_dpp v128, v81, v80, vcc quad_perm:[1,0,3,2] row_mask:0xf bank_mask:0xf
	v_cndmask_b32_dpp v130, v83, v82, vcc quad_perm:[1,0,3,2] row_mask:0xf bank_mask:0xf
	v_cndmask_b32_dpp v112, v97, v96, vcc quad_perm:[1,0,3,2] row_mask:0xf bank_mask:0xf
	v_cndmask_b32_dpp v114, v99, v98, vcc quad_perm:[1,0,3,2] row_mask:0xf bank_mask:0xf
	v_cndmask_b32_dpp v132, v85, v84, vcc quad_perm:[1,0,3,2] row_mask:0xf bank_mask:0xf
	v_cndmask_b32_dpp v134, v87, v86, vcc quad_perm:[1,0,3,2] row_mask:0xf bank_mask:0xf
	v_cndmask_b32_dpp v116, v101, v100, vcc quad_perm:[1,0,3,2] row_mask:0xf bank_mask:0xf
	v_cndmask_b32_dpp v118, v103, v102, vcc quad_perm:[1,0,3,2] row_mask:0xf bank_mask:0xf
	v_cndmask_b32_dpp v136, v89, v88, vcc quad_perm:[1,0,3,2] row_mask:0xf bank_mask:0xf
	v_cndmask_b32_dpp v138, v91, v90, vcc quad_perm:[1,0,3,2] row_mask:0xf bank_mask:0xf
	v_cndmask_b32_dpp v120, v105, v104, vcc quad_perm:[1,0,3,2] row_mask:0xf bank_mask:0xf
	v_cndmask_b32_dpp v122, v107, v106, vcc quad_perm:[1,0,3,2] row_mask:0xf bank_mask:0xf
	v_cndmask_b32_dpp v140, v93, v92, vcc quad_perm:[1,0,3,2] row_mask:0xf bank_mask:0xf
	v_cndmask_b32_dpp v142, v95, v94, vcc quad_perm:[1,0,3,2] row_mask:0xf bank_mask:0xf
	v_cndmask_b32_dpp v124, v109, v108, vcc quad_perm:[1,0,3,2] row_mask:0xf bank_mask:0xf
	v_cndmask_b32_dpp v126, v111, v110, vcc quad_perm:[1,0,3,2] row_mask:0xf bank_mask:0xf
	v_cmp_ne_u32_e32 vcc, 0, v15
	s_nop 1
	v_cndmask_b32_dpp v129, v80, v81, vcc quad_perm:[1,0,3,2] row_mask:0xf bank_mask:0xf
	v_cndmask_b32_dpp v131, v82, v83, vcc quad_perm:[1,0,3,2] row_mask:0xf bank_mask:0xf
	v_cndmask_b32_dpp v113, v96, v97, vcc quad_perm:[1,0,3,2] row_mask:0xf bank_mask:0xf
	v_cndmask_b32_dpp v115, v98, v99, vcc quad_perm:[1,0,3,2] row_mask:0xf bank_mask:0xf
	v_cndmask_b32_dpp v133, v84, v85, vcc quad_perm:[1,0,3,2] row_mask:0xf bank_mask:0xf
	v_cndmask_b32_dpp v135, v86, v87, vcc quad_perm:[1,0,3,2] row_mask:0xf bank_mask:0xf
	v_cndmask_b32_dpp v117, v100, v101, vcc quad_perm:[1,0,3,2] row_mask:0xf bank_mask:0xf
	v_cndmask_b32_dpp v119, v102, v103, vcc quad_perm:[1,0,3,2] row_mask:0xf bank_mask:0xf
	v_cndmask_b32_dpp v137, v88, v89, vcc quad_perm:[1,0,3,2] row_mask:0xf bank_mask:0xf
	v_cndmask_b32_dpp v139, v90, v91, vcc quad_perm:[1,0,3,2] row_mask:0xf bank_mask:0xf
	v_cndmask_b32_dpp v121, v104, v105, vcc quad_perm:[1,0,3,2] row_mask:0xf bank_mask:0xf
	v_cndmask_b32_dpp v123, v106, v107, vcc quad_perm:[1,0,3,2] row_mask:0xf bank_mask:0xf
	v_cndmask_b32_dpp v141, v92, v93, vcc quad_perm:[1,0,3,2] row_mask:0xf bank_mask:0xf
	v_cndmask_b32_dpp v143, v94, v95, vcc quad_perm:[1,0,3,2] row_mask:0xf bank_mask:0xf
	v_cndmask_b32_dpp v125, v108, v109, vcc quad_perm:[1,0,3,2] row_mask:0xf bank_mask:0xf
	v_cndmask_b32_dpp v127, v110, v111, vcc quad_perm:[1,0,3,2] row_mask:0xf bank_mask:0xf
	v_and_b32_e32 v15, 2, v235
	v_cmp_eq_u32_e32 vcc, 0, v15
	s_nop 1
	v_cndmask_b32_dpp v80, v130, v128, vcc quad_perm:[2,3,0,1] row_mask:0xf bank_mask:0xf
	v_cndmask_b32_dpp v81, v131, v129, vcc quad_perm:[2,3,0,1] row_mask:0xf bank_mask:0xf
	v_cndmask_b32_dpp v96, v114, v112, vcc quad_perm:[2,3,0,1] row_mask:0xf bank_mask:0xf
	v_cndmask_b32_dpp v97, v115, v113, vcc quad_perm:[2,3,0,1] row_mask:0xf bank_mask:0xf
	v_cndmask_b32_dpp v84, v134, v132, vcc quad_perm:[2,3,0,1] row_mask:0xf bank_mask:0xf
	v_cndmask_b32_dpp v85, v135, v133, vcc quad_perm:[2,3,0,1] row_mask:0xf bank_mask:0xf
	v_cndmask_b32_dpp v100, v118, v116, vcc quad_perm:[2,3,0,1] row_mask:0xf bank_mask:0xf
	v_cndmask_b32_dpp v101, v119, v117, vcc quad_perm:[2,3,0,1] row_mask:0xf bank_mask:0xf
	v_cndmask_b32_dpp v88, v138, v136, vcc quad_perm:[2,3,0,1] row_mask:0xf bank_mask:0xf
	v_cndmask_b32_dpp v89, v139, v137, vcc quad_perm:[2,3,0,1] row_mask:0xf bank_mask:0xf
	v_cndmask_b32_dpp v104, v122, v120, vcc quad_perm:[2,3,0,1] row_mask:0xf bank_mask:0xf
	v_cndmask_b32_dpp v105, v123, v121, vcc quad_perm:[2,3,0,1] row_mask:0xf bank_mask:0xf
	v_cndmask_b32_dpp v92, v142, v140, vcc quad_perm:[2,3,0,1] row_mask:0xf bank_mask:0xf
	v_cndmask_b32_dpp v93, v143, v141, vcc quad_perm:[2,3,0,1] row_mask:0xf bank_mask:0xf
	v_cndmask_b32_dpp v108, v126, v124, vcc quad_perm:[2,3,0,1] row_mask:0xf bank_mask:0xf
	v_cndmask_b32_dpp v109, v127, v125, vcc quad_perm:[2,3,0,1] row_mask:0xf bank_mask:0xf
	v_cmp_ne_u32_e32 vcc, 0, v15
	s_nop 1
	v_cndmask_b32_dpp v82, v128, v130, vcc quad_perm:[2,3,0,1] row_mask:0xf bank_mask:0xf
	v_cndmask_b32_dpp v83, v129, v131, vcc quad_perm:[2,3,0,1] row_mask:0xf bank_mask:0xf
	v_cndmask_b32_dpp v98, v112, v114, vcc quad_perm:[2,3,0,1] row_mask:0xf bank_mask:0xf
	v_cndmask_b32_dpp v99, v113, v115, vcc quad_perm:[2,3,0,1] row_mask:0xf bank_mask:0xf
	v_cndmask_b32_dpp v86, v132, v134, vcc quad_perm:[2,3,0,1] row_mask:0xf bank_mask:0xf
	v_cndmask_b32_dpp v87, v133, v135, vcc quad_perm:[2,3,0,1] row_mask:0xf bank_mask:0xf
	v_cndmask_b32_dpp v102, v116, v118, vcc quad_perm:[2,3,0,1] row_mask:0xf bank_mask:0xf
	v_cndmask_b32_dpp v103, v117, v119, vcc quad_perm:[2,3,0,1] row_mask:0xf bank_mask:0xf
	v_cndmask_b32_dpp v90, v136, v138, vcc quad_perm:[2,3,0,1] row_mask:0xf bank_mask:0xf
	v_cndmask_b32_dpp v91, v137, v139, vcc quad_perm:[2,3,0,1] row_mask:0xf bank_mask:0xf
	v_cndmask_b32_dpp v106, v120, v122, vcc quad_perm:[2,3,0,1] row_mask:0xf bank_mask:0xf
	v_cndmask_b32_dpp v107, v121, v123, vcc quad_perm:[2,3,0,1] row_mask:0xf bank_mask:0xf
	v_cndmask_b32_dpp v94, v140, v142, vcc quad_perm:[2,3,0,1] row_mask:0xf bank_mask:0xf
	v_cndmask_b32_dpp v95, v141, v143, vcc quad_perm:[2,3,0,1] row_mask:0xf bank_mask:0xf
	v_cndmask_b32_dpp v110, v124, v126, vcc quad_perm:[2,3,0,1] row_mask:0xf bank_mask:0xf
	v_cndmask_b32_dpp v111, v125, v127, vcc quad_perm:[2,3,0,1] row_mask:0xf bank_mask:0xf
	v_cvt_pk_bf16_f32 v128, v80, v81
	v_cvt_pk_bf16_f32 v129, v82, v83
	global_store_dwordx2 v[196:197], v[128:129], off
	v_cvt_pk_bf16_f32 v112, v96, v97
	v_cvt_pk_bf16_f32 v113, v98, v99
	global_store_dwordx2 v[196:197], v[112:113], off offset:64
	v_cvt_pk_bf16_f32 v132, v84, v85
	v_cvt_pk_bf16_f32 v133, v86, v87
	v_add_co_u32_e32 v134, vcc, 0x40000, v196
	s_nop 1
	v_addc_co_u32_e32 v135, vcc, 0, v197, vcc
	global_store_dwordx2 v[134:135], v[132:133], off
	v_cvt_pk_bf16_f32 v116, v100, v101
	v_cvt_pk_bf16_f32 v117, v102, v103
	v_add_co_u32_e32 v118, vcc, 0x40000, v196
	s_nop 1
	v_addc_co_u32_e32 v119, vcc, 0, v197, vcc
	global_store_dwordx2 v[118:119], v[116:117], off offset:64
	v_cvt_pk_bf16_f32 v136, v88, v89
	v_cvt_pk_bf16_f32 v137, v90, v91
	v_add_co_u32_e32 v138, vcc, 0x80000, v196
	s_nop 1
	v_addc_co_u32_e32 v139, vcc, 0, v197, vcc
	global_store_dwordx2 v[138:139], v[136:137], off
	v_cvt_pk_bf16_f32 v120, v104, v105
	v_cvt_pk_bf16_f32 v121, v106, v107
	v_add_co_u32_e32 v122, vcc, 0x80000, v196
	s_nop 1
	v_addc_co_u32_e32 v123, vcc, 0, v197, vcc
	global_store_dwordx2 v[122:123], v[120:121], off offset:64
	v_cvt_pk_bf16_f32 v140, v92, v93
	v_cvt_pk_bf16_f32 v141, v94, v95
	v_add_co_u32_e32 v142, vcc, 0xc0000, v196
	s_nop 1
	v_addc_co_u32_e32 v143, vcc, 0, v197, vcc
	global_store_dwordx2 v[142:143], v[140:141], off
	v_cvt_pk_bf16_f32 v124, v108, v109
	v_cvt_pk_bf16_f32 v125, v110, v111
	v_add_co_u32_e32 v126, vcc, 0xc0000, v196
	s_nop 1
	v_addc_co_u32_e32 v127, vcc, 0, v197, vcc
	global_store_dwordx2 v[126:127], v[124:125], off offset:64
	v_lshl_add_u32 v15, v215, 4, 0
	v_add_u32_e32 v15, 0x17400, v15
	ds_read_b128 v[80:83], v15
	ds_read_b128 v[84:87], v15 offset:32
	ds_read_b128 v[88:91], v15 offset:64
	ds_read_b128 v[92:95], v15 offset:96
	s_waitcnt lgkmcnt(0)
	v_pk_mul_f32 v[18:19], v[18:19], v[82:83]
	v_pk_mul_f32 v[22:23], v[22:23], v[86:87]
	v_pk_mul_f32 v[26:27], v[26:27], v[90:91]
	v_pk_mul_f32 v[30:31], v[30:31], v[94:95]
	v_pk_mul_f32 v[28:29], v[28:29], v[92:93]
	v_pk_mul_f32 v[24:25], v[24:25], v[88:89]
	v_pk_mul_f32 v[20:21], v[20:21], v[84:85]
	v_pk_mul_f32 v[16:17], v[16:17], v[80:81]
	ds_read_b128 v[80:83], v15 offset:128
	ds_read_b128 v[84:87], v15 offset:160
	ds_read_b128 v[88:91], v15 offset:192
	ds_read_b128 v[92:95], v15 offset:224
	s_waitcnt lgkmcnt(0)
	v_pk_mul_f32 v[34:35], v[34:35], v[82:83]
	v_pk_mul_f32 v[38:39], v[38:39], v[86:87]
	v_pk_mul_f32 v[42:43], v[42:43], v[90:91]
	v_pk_mul_f32 v[46:47], v[46:47], v[94:95]
	v_pk_mul_f32 v[44:45], v[44:45], v[92:93]
	v_pk_mul_f32 v[40:41], v[40:41], v[88:89]
	v_pk_mul_f32 v[36:37], v[36:37], v[84:85]
	v_pk_mul_f32 v[32:33], v[32:33], v[80:81]
	ds_read_b128 v[80:83], v15 offset:256
	ds_read_b128 v[84:87], v15 offset:288
	ds_read_b128 v[88:91], v15 offset:320
	ds_read_b128 v[92:95], v15 offset:352
	s_waitcnt lgkmcnt(0)
	v_pk_mul_f32 v[50:51], v[50:51], v[82:83]
	v_pk_mul_f32 v[54:55], v[54:55], v[86:87]
	v_pk_mul_f32 v[58:59], v[58:59], v[90:91]
	v_pk_mul_f32 v[62:63], v[62:63], v[94:95]
	v_pk_mul_f32 v[60:61], v[60:61], v[92:93]
	v_pk_mul_f32 v[56:57], v[56:57], v[88:89]
	v_pk_mul_f32 v[52:53], v[52:53], v[84:85]
	v_pk_mul_f32 v[48:49], v[48:49], v[80:81]
	ds_read_b128 v[80:83], v15 offset:384
	ds_read_b128 v[84:87], v15 offset:416
	ds_read_b128 v[88:91], v15 offset:448
	ds_read_b128 v[92:95], v15 offset:480
	v_add_u32_e32 v15, s76, v14
	s_waitcnt lgkmcnt(0)
	v_pk_mul_f32 v[64:65], v[64:65], v[80:81]
	v_mad_u64_u32 v[80:81], s[0:1], v15, s53, v[0:1]
	v_mul_lo_u32 v14, v14, s63
	v_lshl_add_u32 v15, v80, 1, 0
	v_add_u32_e32 v80, v0, v14
	v_lshl_add_u32 v80, v80, 1, 0
	v_add_u32_e32 v80, 0x8800, v80
	v_pk_mul_f32 v[74:75], v[74:75], v[90:91]
	v_pk_mul_f32 v[70:71], v[70:71], v[86:87]
	v_pk_mul_f32 v[66:67], v[66:67], v[82:83]
	v_pk_mul_f32 v[72:73], v[72:73], v[88:89]
	v_pk_mul_f32 v[68:69], v[68:69], v[84:85]
	ds_read2_b64 v[80:83], v80 offset1:1
	ds_read_b128 v[84:87], v15 offset:52224
	ds_read_b128 v[88:91], v15 offset:52256
	v_pk_mul_f32 v[76:77], v[76:77], v[92:93]
	v_add_u32_e32 v92, 0x880, v14
	s_waitcnt lgkmcnt(0)
	v_mfma_f32_32x32x16_bf16 v[16:31], v[80:83], v[84:87], v[16:31]
	v_add_u32_e32 v80, v92, v0
	v_lshl_add_u32 v80, v80, 1, 0
	v_add_u32_e32 v80, 0x8800, v80
	ds_read2_b64 v[80:83], v80 offset1:1
	v_add_u32_e32 v93, 0x1100, v14
	v_pk_mul_f32 v[78:79], v[78:79], v[94:95]
	v_add_u32_e32 v94, 0x1980, v14
	s_waitcnt lgkmcnt(0)
	v_mfma_f32_32x32x16_bf16 v[32:47], v[80:83], v[84:87], v[32:47]
	v_add_u32_e32 v80, v93, v0
	v_lshl_add_u32 v80, v80, 1, 0
	v_add_u32_e32 v80, 0x8800, v80
	ds_read2_b64 v[80:83], v80 offset1:1
	s_waitcnt lgkmcnt(0)
	v_mfma_f32_32x32x16_bf16 v[48:63], v[80:83], v[84:87], v[48:63]
	v_add_u32_e32 v80, v94, v0
	v_lshl_add_u32 v80, v80, 1, 0
	v_add_u32_e32 v80, 0x8800, v80
	ds_read2_b64 v[80:83], v80 offset1:1
	s_waitcnt lgkmcnt(0)
	v_mfma_f32_32x32x16_bf16 v[64:79], v[80:83], v[84:87], v[64:79]
	v_add_u32_e32 v84, 16, v0
	v_add_u32_e32 v80, v84, v14
	v_lshl_add_u32 v80, v80, 1, 0
	v_add_u32_e32 v80, 0x8800, v80
	ds_read2_b64 v[80:83], v80 offset1:1
	s_waitcnt lgkmcnt(0)
	v_mfma_f32_32x32x16_bf16 v[16:31], v[80:83], v[88:91], v[16:31]
	v_add_u32_e32 v80, v84, v92
	v_lshl_add_u32 v80, v80, 1, 0
	v_add_u32_e32 v80, 0x8800, v80
	ds_read2_b64 v[80:83], v80 offset1:1
	s_waitcnt lgkmcnt(0)
	v_mfma_f32_32x32x16_bf16 v[32:47], v[80:83], v[88:91], v[32:47]
	v_add_u32_e32 v80, v84, v93
	v_lshl_add_u32 v80, v80, 1, 0
	v_add_u32_e32 v80, 0x8800, v80
	ds_read2_b64 v[80:83], v80 offset1:1
	s_waitcnt lgkmcnt(0)
	v_mfma_f32_32x32x16_bf16 v[48:63], v[80:83], v[88:91], v[48:63]
	v_add_u32_e32 v80, v84, v94
	v_lshl_add_u32 v80, v80, 1, 0
	v_add_u32_e32 v80, 0x8800, v80
	ds_read2_b64 v[80:83], v80 offset1:1
	s_waitcnt lgkmcnt(0)
	v_mfma_f32_32x32x16_bf16 v[64:79], v[80:83], v[88:91], v[64:79]
	v_add_u32_e32 v88, 32, v0
	v_add_u32_e32 v84, v88, v14
	v_lshl_add_u32 v84, v84, 1, 0
	v_add_u32_e32 v84, 0x8800, v84
	ds_read_b128 v[80:83], v15 offset:52288
	ds_read2_b64 v[84:87], v84 offset1:1
	v_add_u32_e32 v0, 48, v0
	s_waitcnt lgkmcnt(0)
	v_mfma_f32_32x32x16_bf16 v[16:31], v[84:87], v[80:83], v[16:31]
	v_add_u32_e32 v84, v88, v92
	v_lshl_add_u32 v84, v84, 1, 0
	v_add_u32_e32 v84, 0x8800, v84
	ds_read2_b64 v[84:87], v84 offset1:1
	v_add_u32_e32 v14, v0, v14
	v_lshl_add_u32 v14, v14, 1, 0
	v_add_u32_e32 v14, 0x8800, v14
	s_waitcnt lgkmcnt(0)
	v_mfma_f32_32x32x16_bf16 v[32:47], v[84:87], v[80:83], v[32:47]
	v_add_u32_e32 v84, v88, v93
	v_lshl_add_u32 v84, v84, 1, 0
	v_add_u32_e32 v84, 0x8800, v84
	ds_read2_b64 v[84:87], v84 offset1:1
	s_waitcnt lgkmcnt(0)
	v_mfma_f32_32x32x16_bf16 v[48:63], v[84:87], v[80:83], v[48:63]
	v_add_u32_e32 v84, v88, v94
	v_lshl_add_u32 v84, v84, 1, 0
	v_add_u32_e32 v84, 0x8800, v84
	ds_read2_b64 v[84:87], v84 offset1:1
	s_waitcnt lgkmcnt(0)
	v_mfma_f32_32x32x16_bf16 v[64:79], v[84:87], v[80:83], v[64:79]
	ds_read_b128 v[80:83], v15 offset:52320
	ds_read2_b64 v[84:87], v14 offset1:1
	v_add_u32_e32 v14, v0, v92
	v_lshl_add_u32 v14, v14, 1, 0
	v_add_u32_e32 v14, 0x8800, v14
	s_waitcnt lgkmcnt(0)
	v_mfma_f32_32x32x16_bf16 v[16:31], v[84:87], v[80:83], v[16:31]
	ds_read2_b64 v[84:87], v14 offset1:1
	v_add_u32_e32 v14, v0, v93
	v_lshl_add_u32 v14, v14, 1, 0
	v_add_u32_e32 v14, 0x8800, v14
	v_add_u32_e32 v0, v0, v94
	v_lshl_add_u32 v0, v0, 1, 0
	v_add_u32_e32 v0, 0x8800, v0
	s_waitcnt lgkmcnt(0)
	v_mfma_f32_32x32x16_bf16 v[32:47], v[84:87], v[80:83], v[32:47]
	ds_read2_b64 v[84:87], v14 offset1:1
	s_waitcnt lgkmcnt(0)
	v_mfma_f32_32x32x16_bf16 v[48:63], v[84:87], v[80:83], v[48:63]
	ds_read2_b64 v[84:87], v0 offset1:1
	s_waitcnt lgkmcnt(0)
	v_mfma_f32_32x32x16_bf16 v[64:79], v[84:87], v[80:83], v[64:79]
	s_cbranch_scc1 .LBB0_505

.LBB0_500:
	v_lshlrev_b32_e32 v0, 3, v215
	v_mul_lo_u32 v15, v14, s64
	v_add3_u32 v15, 0, v0, v15
	v_cvt_pk_bf16_f32 v96, v16, v17
	v_cvt_pk_bf16_f32 v97, v18, v19
	v_cvt_pk_bf16_f32 v98, v20, v21
	v_cvt_pk_bf16_f32 v99, v22, v23
	ds_read2_b64 v[80:83], v15 offset1:2
	ds_read2_b64 v[238:241], v15 offset0:4 offset1:6
	v_add_u32_e32 v196, 0x2000, v15
	s_waitcnt lgkmcnt(0)
	v_mfma_f32_32x32x16_bf16 v[80:95], v[96:99], v[80:83], 0
	ds_read2_b64 v[100:103], v196 offset0:64 offset1:66
	v_cvt_pk_bf16_f32 v242, v24, v25
	v_cvt_pk_bf16_f32 v243, v26, v27
	v_cvt_pk_bf16_f32 v244, v28, v29
	v_cvt_pk_bf16_f32 v245, v30, v31
	v_cvt_pk_bf16_f32 v112, v32, v33
	v_cvt_pk_bf16_f32 v113, v34, v35
	v_cvt_pk_bf16_f32 v114, v36, v37
	v_cvt_pk_bf16_f32 v115, v38, v39
	s_waitcnt lgkmcnt(0)
	v_mfma_f32_32x32x16_bf16 v[96:111], v[96:99], v[100:103], 0
	ds_read2_b64 v[116:119], v15 offset0:8 offset1:10
	v_cvt_pk_bf16_f32 v246, v40, v41
	v_cvt_pk_bf16_f32 v247, v42, v43
	v_cvt_pk_bf16_f32 v248, v44, v45
	v_cvt_pk_bf16_f32 v249, v46, v47
	s_add_i32 s4, s79, -3
	s_add_i32 s5, s78, 3
	v_mfma_f32_32x32x16_bf16 v[80:95], v[242:245], v[238:241], v[80:95]
	ds_read2_b64 v[238:241], v196 offset0:68 offset1:70
	s_and_b64 s[0:1], s[34:35], exec
	s_cselect_b32 s0, s4, s5
	s_lshl_b32 s0, s0, 6
	s_add_i32 s38, s0, s44
	s_ashr_i32 s39, s38, 31
	s_waitcnt lgkmcnt(0)
	v_mfma_f32_32x32x16_bf16 v[128:143], v[112:115], v[116:119], 0
	ds_read2_b64 v[116:119], v196 offset0:72 offset1:74
	v_mfma_f32_32x32x16_bf16 v[96:111], v[242:245], v[238:241], v[96:111]
	ds_read2_b64 v[238:241], v15 offset0:12 offset1:14
	v_cvt_pk_bf16_f32 v242, v64, v65
	v_cvt_pk_bf16_f32 v243, v66, v67
	v_cvt_pk_bf16_f32 v244, v68, v69
	v_cvt_pk_bf16_f32 v245, v70, v71
	s_waitcnt lgkmcnt(0)
	v_mfma_f32_32x32x16_bf16 v[112:127], v[112:115], v[116:119], 0
	v_mfma_f32_32x32x16_bf16 v[128:143], v[246:249], v[238:241], v[128:143]
	ds_read2_b64 v[238:241], v196 offset0:76 offset1:78
	s_waitcnt lgkmcnt(0)
	v_mfma_f32_32x32x16_bf16 v[112:127], v[246:249], v[238:241], v[112:127]
	v_cvt_pk_bf16_f32 v238, v48, v49
	v_cvt_pk_bf16_f32 v239, v50, v51
	v_cvt_pk_bf16_f32 v240, v52, v53
	v_cvt_pk_bf16_f32 v241, v54, v55
	ds_read2_b64 v[246:249], v15 offset0:16 offset1:18
	s_waitcnt lgkmcnt(0)
	v_mfma_f32_32x32x16_bf16 v[80:95], v[238:241], v[246:249], v[80:95]
	ds_read2_b64 v[246:249], v196 offset0:80 offset1:82
	s_waitcnt lgkmcnt(0)
	v_mfma_f32_32x32x16_bf16 v[96:111], v[238:241], v[246:249], v[96:111]
	ds_read2_b64 v[238:241], v15 offset0:24 offset1:26
	ds_read2_b64 v[246:249], v15 offset0:20 offset1:22
	s_waitcnt lgkmcnt(0)
	v_mfma_f32_32x32x16_bf16 v[128:143], v[242:245], v[238:241], v[128:143]
	ds_read2_b64 v[238:241], v196 offset0:88 offset1:90
	s_waitcnt lgkmcnt(0)
	v_mfma_f32_32x32x16_bf16 v[112:127], v[242:245], v[238:241], v[112:127]
	v_cvt_pk_bf16_f32 v238, v56, v57
	v_cvt_pk_bf16_f32 v239, v58, v59
	v_cvt_pk_bf16_f32 v240, v60, v61
	v_cvt_pk_bf16_f32 v241, v62, v63
	v_cvt_pk_bf16_f32 v242, v72, v73
	v_cvt_pk_bf16_f32 v243, v74, v75
	v_cvt_pk_bf16_f32 v244, v76, v77
	v_mfma_f32_32x32x16_bf16 v[80:95], v[238:241], v[246:249], v[80:95]
	ds_read2_b64 v[246:249], v196 offset0:84 offset1:86
	v_cvt_pk_bf16_f32 v245, v78, v79
	s_waitcnt lgkmcnt(0)
	v_mfma_f32_32x32x16_bf16 v[96:111], v[238:241], v[246:249], v[96:111]
	ds_read2_b64 v[238:241], v15 offset0:28 offset1:30
	v_ashrrev_i32_e32 v15, 31, v14
	s_waitcnt lgkmcnt(0)
	v_mfma_f32_32x32x16_bf16 v[128:143], v[242:245], v[238:241], v[128:143]
	ds_read2_b64 v[238:241], v196 offset0:92 offset1:94
	v_lshl_add_u32 v196, v215, 2, s71
	v_ashrrev_i32_e32 v197, 31, v196
	v_lshlrev_b64 v[196:197], 15, v[196:197]
	v_lshl_add_u64 v[196:197], s[68:69], 0, v[196:197]
	v_lshl_add_u64 v[196:197], s[38:39], 1, v[196:197]
	v_lshl_add_u64 v[196:197], v[14:15], 1, v[196:197]
	s_waitcnt lgkmcnt(0)
	v_mfma_f32_32x32x16_bf16 v[112:127], v[242:245], v[238:241], v[112:127]
	s_nop 7
	s_nop 3
	v_add_f32_e32 v80, v80, v128
	v_add_f32_e32 v81, v81, v129
	v_add_f32_e32 v82, v82, v130
	v_add_f32_e32 v83, v83, v131
	v_add_f32_e32 v84, v84, v132
	v_add_f32_e32 v85, v85, v133
	v_add_f32_e32 v86, v86, v134
	v_add_f32_e32 v87, v87, v135
	v_add_f32_e32 v88, v88, v136
	v_add_f32_e32 v89, v89, v137
	v_add_f32_e32 v90, v90, v138
	v_add_f32_e32 v91, v91, v139
	v_add_f32_e32 v92, v92, v140
	v_add_f32_e32 v93, v93, v141
	v_add_f32_e32 v94, v94, v142
	v_add_f32_e32 v95, v95, v143
	v_add_f32_e32 v96, v96, v112
	v_add_f32_e32 v97, v97, v113
	v_add_f32_e32 v98, v98, v114
	v_add_f32_e32 v99, v99, v115
	v_add_f32_e32 v100, v100, v116
	v_add_f32_e32 v101, v101, v117
	v_add_f32_e32 v102, v102, v118
	v_add_f32_e32 v103, v103, v119
	v_add_f32_e32 v104, v104, v120
	v_add_f32_e32 v105, v105, v121
	v_add_f32_e32 v106, v106, v122
	v_add_f32_e32 v107, v107, v123
	v_add_f32_e32 v108, v108, v124
	v_add_f32_e32 v109, v109, v125
	v_add_f32_e32 v110, v110, v126
	v_add_f32_e32 v111, v111, v127
	v_and_b32_e32 v15, 3, v235
	v_mul_u32_u24_e32 v15, 0x7ffe, v15
	v_add_co_u32_e32 v196, vcc, v196, v15
	s_nop 1
	v_addc_co_u32_e32 v197, vcc, 0, v197, vcc
	v_and_b32_e32 v15, 1, v235
	v_cmp_eq_u32_e32 vcc, 0, v15
	s_nop 1
	v_cndmask_b32_dpp v128, v81, v80, vcc quad_perm:[1,0,3,2] row_mask:0xf bank_mask:0xf
	v_cndmask_b32_dpp v130, v83, v82, vcc quad_perm:[1,0,3,2] row_mask:0xf bank_mask:0xf
	v_cndmask_b32_dpp v112, v97, v96, vcc quad_perm:[1,0,3,2] row_mask:0xf bank_mask:0xf
	v_cndmask_b32_dpp v114, v99, v98, vcc quad_perm:[1,0,3,2] row_mask:0xf bank_mask:0xf
	v_cndmask_b32_dpp v132, v85, v84, vcc quad_perm:[1,0,3,2] row_mask:0xf bank_mask:0xf
	v_cndmask_b32_dpp v134, v87, v86, vcc quad_perm:[1,0,3,2] row_mask:0xf bank_mask:0xf
	v_cndmask_b32_dpp v116, v101, v100, vcc quad_perm:[1,0,3,2] row_mask:0xf bank_mask:0xf
	v_cndmask_b32_dpp v118, v103, v102, vcc quad_perm:[1,0,3,2] row_mask:0xf bank_mask:0xf
	v_cndmask_b32_dpp v136, v89, v88, vcc quad_perm:[1,0,3,2] row_mask:0xf bank_mask:0xf
	v_cndmask_b32_dpp v138, v91, v90, vcc quad_perm:[1,0,3,2] row_mask:0xf bank_mask:0xf
	v_cndmask_b32_dpp v120, v105, v104, vcc quad_perm:[1,0,3,2] row_mask:0xf bank_mask:0xf
	v_cndmask_b32_dpp v122, v107, v106, vcc quad_perm:[1,0,3,2] row_mask:0xf bank_mask:0xf
	v_cndmask_b32_dpp v140, v93, v92, vcc quad_perm:[1,0,3,2] row_mask:0xf bank_mask:0xf
	v_cndmask_b32_dpp v142, v95, v94, vcc quad_perm:[1,0,3,2] row_mask:0xf bank_mask:0xf
	v_cndmask_b32_dpp v124, v109, v108, vcc quad_perm:[1,0,3,2] row_mask:0xf bank_mask:0xf
	v_cndmask_b32_dpp v126, v111, v110, vcc quad_perm:[1,0,3,2] row_mask:0xf bank_mask:0xf
	v_cmp_ne_u32_e32 vcc, 0, v15
	s_nop 1
	v_cndmask_b32_dpp v129, v80, v81, vcc quad_perm:[1,0,3,2] row_mask:0xf bank_mask:0xf
	v_cndmask_b32_dpp v131, v82, v83, vcc quad_perm:[1,0,3,2] row_mask:0xf bank_mask:0xf
	v_cndmask_b32_dpp v113, v96, v97, vcc quad_perm:[1,0,3,2] row_mask:0xf bank_mask:0xf
	v_cndmask_b32_dpp v115, v98, v99, vcc quad_perm:[1,0,3,2] row_mask:0xf bank_mask:0xf
	v_cndmask_b32_dpp v133, v84, v85, vcc quad_perm:[1,0,3,2] row_mask:0xf bank_mask:0xf
	v_cndmask_b32_dpp v135, v86, v87, vcc quad_perm:[1,0,3,2] row_mask:0xf bank_mask:0xf
	v_cndmask_b32_dpp v117, v100, v101, vcc quad_perm:[1,0,3,2] row_mask:0xf bank_mask:0xf
	v_cndmask_b32_dpp v119, v102, v103, vcc quad_perm:[1,0,3,2] row_mask:0xf bank_mask:0xf
	v_cndmask_b32_dpp v137, v88, v89, vcc quad_perm:[1,0,3,2] row_mask:0xf bank_mask:0xf
	v_cndmask_b32_dpp v139, v90, v91, vcc quad_perm:[1,0,3,2] row_mask:0xf bank_mask:0xf
	v_cndmask_b32_dpp v121, v104, v105, vcc quad_perm:[1,0,3,2] row_mask:0xf bank_mask:0xf
	v_cndmask_b32_dpp v123, v106, v107, vcc quad_perm:[1,0,3,2] row_mask:0xf bank_mask:0xf
	v_cndmask_b32_dpp v141, v92, v93, vcc quad_perm:[1,0,3,2] row_mask:0xf bank_mask:0xf
	v_cndmask_b32_dpp v143, v94, v95, vcc quad_perm:[1,0,3,2] row_mask:0xf bank_mask:0xf
	v_cndmask_b32_dpp v125, v108, v109, vcc quad_perm:[1,0,3,2] row_mask:0xf bank_mask:0xf
	v_cndmask_b32_dpp v127, v110, v111, vcc quad_perm:[1,0,3,2] row_mask:0xf bank_mask:0xf
	v_and_b32_e32 v15, 2, v235
	v_cmp_eq_u32_e32 vcc, 0, v15
	s_nop 1
	v_cndmask_b32_dpp v80, v130, v128, vcc quad_perm:[2,3,0,1] row_mask:0xf bank_mask:0xf
	v_cndmask_b32_dpp v81, v131, v129, vcc quad_perm:[2,3,0,1] row_mask:0xf bank_mask:0xf
	v_cndmask_b32_dpp v96, v114, v112, vcc quad_perm:[2,3,0,1] row_mask:0xf bank_mask:0xf
	v_cndmask_b32_dpp v97, v115, v113, vcc quad_perm:[2,3,0,1] row_mask:0xf bank_mask:0xf
	v_cndmask_b32_dpp v84, v134, v132, vcc quad_perm:[2,3,0,1] row_mask:0xf bank_mask:0xf
	v_cndmask_b32_dpp v85, v135, v133, vcc quad_perm:[2,3,0,1] row_mask:0xf bank_mask:0xf
	v_cndmask_b32_dpp v100, v118, v116, vcc quad_perm:[2,3,0,1] row_mask:0xf bank_mask:0xf
	v_cndmask_b32_dpp v101, v119, v117, vcc quad_perm:[2,3,0,1] row_mask:0xf bank_mask:0xf
	v_cndmask_b32_dpp v88, v138, v136, vcc quad_perm:[2,3,0,1] row_mask:0xf bank_mask:0xf
	v_cndmask_b32_dpp v89, v139, v137, vcc quad_perm:[2,3,0,1] row_mask:0xf bank_mask:0xf
	v_cndmask_b32_dpp v104, v122, v120, vcc quad_perm:[2,3,0,1] row_mask:0xf bank_mask:0xf
	v_cndmask_b32_dpp v105, v123, v121, vcc quad_perm:[2,3,0,1] row_mask:0xf bank_mask:0xf
	v_cndmask_b32_dpp v92, v142, v140, vcc quad_perm:[2,3,0,1] row_mask:0xf bank_mask:0xf
	v_cndmask_b32_dpp v93, v143, v141, vcc quad_perm:[2,3,0,1] row_mask:0xf bank_mask:0xf
	v_cndmask_b32_dpp v108, v126, v124, vcc quad_perm:[2,3,0,1] row_mask:0xf bank_mask:0xf
	v_cndmask_b32_dpp v109, v127, v125, vcc quad_perm:[2,3,0,1] row_mask:0xf bank_mask:0xf
	v_cmp_ne_u32_e32 vcc, 0, v15
	s_nop 1
	v_cndmask_b32_dpp v82, v128, v130, vcc quad_perm:[2,3,0,1] row_mask:0xf bank_mask:0xf
	v_cndmask_b32_dpp v83, v129, v131, vcc quad_perm:[2,3,0,1] row_mask:0xf bank_mask:0xf
	v_cndmask_b32_dpp v98, v112, v114, vcc quad_perm:[2,3,0,1] row_mask:0xf bank_mask:0xf
	v_cndmask_b32_dpp v99, v113, v115, vcc quad_perm:[2,3,0,1] row_mask:0xf bank_mask:0xf
	v_cndmask_b32_dpp v86, v132, v134, vcc quad_perm:[2,3,0,1] row_mask:0xf bank_mask:0xf
	v_cndmask_b32_dpp v87, v133, v135, vcc quad_perm:[2,3,0,1] row_mask:0xf bank_mask:0xf
	v_cndmask_b32_dpp v102, v116, v118, vcc quad_perm:[2,3,0,1] row_mask:0xf bank_mask:0xf
	v_cndmask_b32_dpp v103, v117, v119, vcc quad_perm:[2,3,0,1] row_mask:0xf bank_mask:0xf
	v_cndmask_b32_dpp v90, v136, v138, vcc quad_perm:[2,3,0,1] row_mask:0xf bank_mask:0xf
	v_cndmask_b32_dpp v91, v137, v139, vcc quad_perm:[2,3,0,1] row_mask:0xf bank_mask:0xf
	v_cndmask_b32_dpp v106, v120, v122, vcc quad_perm:[2,3,0,1] row_mask:0xf bank_mask:0xf
	v_cndmask_b32_dpp v107, v121, v123, vcc quad_perm:[2,3,0,1] row_mask:0xf bank_mask:0xf
	v_cndmask_b32_dpp v94, v140, v142, vcc quad_perm:[2,3,0,1] row_mask:0xf bank_mask:0xf
	v_cndmask_b32_dpp v95, v141, v143, vcc quad_perm:[2,3,0,1] row_mask:0xf bank_mask:0xf
	v_cndmask_b32_dpp v110, v124, v126, vcc quad_perm:[2,3,0,1] row_mask:0xf bank_mask:0xf
	v_cndmask_b32_dpp v111, v125, v127, vcc quad_perm:[2,3,0,1] row_mask:0xf bank_mask:0xf
	v_cvt_pk_bf16_f32 v128, v80, v81
	v_cvt_pk_bf16_f32 v129, v82, v83
	global_store_dwordx2 v[196:197], v[128:129], off
	v_cvt_pk_bf16_f32 v112, v96, v97
	v_cvt_pk_bf16_f32 v113, v98, v99
	global_store_dwordx2 v[196:197], v[112:113], off offset:64
	v_cvt_pk_bf16_f32 v132, v84, v85
	v_cvt_pk_bf16_f32 v133, v86, v87
	v_add_co_u32_e32 v134, vcc, 0x40000, v196
	s_nop 1
	v_addc_co_u32_e32 v135, vcc, 0, v197, vcc
	global_store_dwordx2 v[134:135], v[132:133], off
	v_cvt_pk_bf16_f32 v116, v100, v101
	v_cvt_pk_bf16_f32 v117, v102, v103
	v_add_co_u32_e32 v118, vcc, 0x40000, v196
	s_nop 1
	v_addc_co_u32_e32 v119, vcc, 0, v197, vcc
	global_store_dwordx2 v[118:119], v[116:117], off offset:64
	v_cvt_pk_bf16_f32 v136, v88, v89
	v_cvt_pk_bf16_f32 v137, v90, v91
	v_add_co_u32_e32 v138, vcc, 0x80000, v196
	s_nop 1
	v_addc_co_u32_e32 v139, vcc, 0, v197, vcc
	global_store_dwordx2 v[138:139], v[136:137], off
	v_cvt_pk_bf16_f32 v120, v104, v105
	v_cvt_pk_bf16_f32 v121, v106, v107
	v_add_co_u32_e32 v122, vcc, 0x80000, v196
	s_nop 1
	v_addc_co_u32_e32 v123, vcc, 0, v197, vcc
	global_store_dwordx2 v[122:123], v[120:121], off offset:64
	v_cvt_pk_bf16_f32 v140, v92, v93
	v_cvt_pk_bf16_f32 v141, v94, v95
	v_add_co_u32_e32 v142, vcc, 0xc0000, v196
	s_nop 1
	v_addc_co_u32_e32 v143, vcc, 0, v197, vcc
	global_store_dwordx2 v[142:143], v[140:141], off
	v_cvt_pk_bf16_f32 v124, v108, v109
	v_cvt_pk_bf16_f32 v125, v110, v111
	v_add_co_u32_e32 v126, vcc, 0xc0000, v196
	s_nop 1
	v_addc_co_u32_e32 v127, vcc, 0, v197, vcc
	global_store_dwordx2 v[126:127], v[124:125], off offset:64
	v_lshl_add_u32 v15, v215, 4, 0
	v_add_u32_e32 v15, 0x17400, v15
	ds_read_b128 v[80:83], v15
	ds_read_b128 v[84:87], v15 offset:32
	ds_read_b128 v[88:91], v15 offset:64
	ds_read_b128 v[92:95], v15 offset:96
	v_mov_b32_e32 v215, v209
	s_waitcnt lgkmcnt(0)
	v_pk_mul_f32 v[18:19], v[18:19], v[82:83]
	v_pk_mul_f32 v[22:23], v[22:23], v[86:87]
	v_pk_mul_f32 v[26:27], v[26:27], v[90:91]
	v_pk_mul_f32 v[30:31], v[30:31], v[94:95]
	v_pk_mul_f32 v[28:29], v[28:29], v[92:93]
	v_pk_mul_f32 v[24:25], v[24:25], v[88:89]
	v_pk_mul_f32 v[20:21], v[20:21], v[84:85]
	v_pk_mul_f32 v[16:17], v[16:17], v[80:81]
	ds_read_b128 v[80:83], v15 offset:128
	ds_read_b128 v[84:87], v15 offset:160
	ds_read_b128 v[88:91], v15 offset:192
	ds_read_b128 v[92:95], v15 offset:224
	s_waitcnt lgkmcnt(0)
	v_pk_mul_f32 v[34:35], v[34:35], v[82:83]
	v_pk_mul_f32 v[38:39], v[38:39], v[86:87]
	v_pk_mul_f32 v[42:43], v[42:43], v[90:91]
	v_pk_mul_f32 v[46:47], v[46:47], v[94:95]
	v_pk_mul_f32 v[44:45], v[44:45], v[92:93]
	v_pk_mul_f32 v[40:41], v[40:41], v[88:89]
	v_pk_mul_f32 v[36:37], v[36:37], v[84:85]
	v_pk_mul_f32 v[32:33], v[32:33], v[80:81]
	ds_read_b128 v[80:83], v15 offset:256
	ds_read_b128 v[84:87], v15 offset:288
	ds_read_b128 v[88:91], v15 offset:320
	ds_read_b128 v[92:95], v15 offset:352
	s_waitcnt lgkmcnt(0)
	v_pk_mul_f32 v[50:51], v[50:51], v[82:83]
	v_pk_mul_f32 v[54:55], v[54:55], v[86:87]
	v_pk_mul_f32 v[58:59], v[58:59], v[90:91]
	v_pk_mul_f32 v[62:63], v[62:63], v[94:95]
	v_pk_mul_f32 v[60:61], v[60:61], v[92:93]
	v_pk_mul_f32 v[56:57], v[56:57], v[88:89]
	v_pk_mul_f32 v[52:53], v[52:53], v[84:85]
	v_pk_mul_f32 v[48:49], v[48:49], v[80:81]
	ds_read_b128 v[80:83], v15 offset:384
	ds_read_b128 v[84:87], v15 offset:416
	ds_read_b128 v[88:91], v15 offset:448
	ds_read_b128 v[92:95], v15 offset:480
	v_add_u32_e32 v15, s76, v14
	s_waitcnt lgkmcnt(0)
	v_pk_mul_f32 v[64:65], v[64:65], v[80:81]
	v_mad_u64_u32 v[80:81], s[0:1], v15, s53, v[0:1]
	v_mul_lo_u32 v14, v14, s63
	v_lshl_add_u32 v15, v80, 1, 0
	v_add_u32_e32 v80, v0, v14
	v_lshl_add_u32 v80, v80, 1, 0
	v_add_u32_e32 v80, 0x8800, v80
	v_pk_mul_f32 v[74:75], v[74:75], v[90:91]
	v_pk_mul_f32 v[70:71], v[70:71], v[86:87]
	v_pk_mul_f32 v[66:67], v[66:67], v[82:83]
	v_pk_mul_f32 v[72:73], v[72:73], v[88:89]
	v_pk_mul_f32 v[68:69], v[68:69], v[84:85]
	ds_read2_b64 v[80:83], v80 offset1:1
	ds_read_b128 v[84:87], v15 offset:52224
	ds_read_b128 v[88:91], v15 offset:52256
	v_pk_mul_f32 v[76:77], v[76:77], v[92:93]
	v_add_u32_e32 v92, 0x880, v14
	s_waitcnt lgkmcnt(0)
	v_mfma_f32_32x32x16_bf16 v[16:31], v[80:83], v[84:87], v[16:31]
	v_add_u32_e32 v80, v92, v0
	v_lshl_add_u32 v80, v80, 1, 0
	v_add_u32_e32 v80, 0x8800, v80
	ds_read2_b64 v[80:83], v80 offset1:1
	v_add_u32_e32 v93, 0x1100, v14
	v_pk_mul_f32 v[78:79], v[78:79], v[94:95]
	v_add_u32_e32 v94, 0x1980, v14
	s_waitcnt lgkmcnt(0)
	v_mfma_f32_32x32x16_bf16 v[32:47], v[80:83], v[84:87], v[32:47]
	v_add_u32_e32 v80, v93, v0
	v_lshl_add_u32 v80, v80, 1, 0
	v_add_u32_e32 v80, 0x8800, v80
	ds_read2_b64 v[80:83], v80 offset1:1
	s_waitcnt lgkmcnt(0)
	v_mfma_f32_32x32x16_bf16 v[48:63], v[80:83], v[84:87], v[48:63]
	v_add_u32_e32 v80, v94, v0
	v_lshl_add_u32 v80, v80, 1, 0
	v_add_u32_e32 v80, 0x8800, v80
	ds_read2_b64 v[80:83], v80 offset1:1
	s_waitcnt lgkmcnt(0)
	v_mfma_f32_32x32x16_bf16 v[64:79], v[80:83], v[84:87], v[64:79]
	v_add_u32_e32 v84, 16, v0
	v_add_u32_e32 v80, v84, v14
	v_lshl_add_u32 v80, v80, 1, 0
	v_add_u32_e32 v80, 0x8800, v80
	ds_read2_b64 v[80:83], v80 offset1:1
	s_waitcnt lgkmcnt(0)
	v_mfma_f32_32x32x16_bf16 v[16:31], v[80:83], v[88:91], v[16:31]
	v_add_u32_e32 v80, v84, v92
	v_lshl_add_u32 v80, v80, 1, 0
	v_add_u32_e32 v80, 0x8800, v80
	ds_read2_b64 v[80:83], v80 offset1:1
	s_waitcnt lgkmcnt(0)
	v_mfma_f32_32x32x16_bf16 v[32:47], v[80:83], v[88:91], v[32:47]
	v_add_u32_e32 v80, v84, v93
	v_lshl_add_u32 v80, v80, 1, 0
	v_add_u32_e32 v80, 0x8800, v80
	ds_read2_b64 v[80:83], v80 offset1:1
	s_waitcnt lgkmcnt(0)
	v_mfma_f32_32x32x16_bf16 v[48:63], v[80:83], v[88:91], v[48:63]
	v_add_u32_e32 v80, v84, v94
	v_lshl_add_u32 v80, v80, 1, 0
	v_add_u32_e32 v80, 0x8800, v80
	ds_read2_b64 v[80:83], v80 offset1:1
	s_waitcnt lgkmcnt(0)
	v_mfma_f32_32x32x16_bf16 v[64:79], v[80:83], v[88:91], v[64:79]
	v_add_u32_e32 v88, 32, v0
	v_add_u32_e32 v84, v88, v14
	v_lshl_add_u32 v84, v84, 1, 0
	v_add_u32_e32 v84, 0x8800, v84
	ds_read_b128 v[80:83], v15 offset:52288
	ds_read2_b64 v[84:87], v84 offset1:1
	v_add_u32_e32 v0, 48, v0
	s_waitcnt lgkmcnt(0)
	v_mfma_f32_32x32x16_bf16 v[16:31], v[84:87], v[80:83], v[16:31]
	v_add_u32_e32 v84, v88, v92
	v_lshl_add_u32 v84, v84, 1, 0
	v_add_u32_e32 v84, 0x8800, v84
	ds_read2_b64 v[84:87], v84 offset1:1
	v_add_u32_e32 v14, v0, v14
	v_lshl_add_u32 v14, v14, 1, 0
	v_add_u32_e32 v14, 0x8800, v14
	s_waitcnt lgkmcnt(0)
	v_mfma_f32_32x32x16_bf16 v[32:47], v[84:87], v[80:83], v[32:47]
	v_add_u32_e32 v84, v88, v93
	v_lshl_add_u32 v84, v84, 1, 0
	v_add_u32_e32 v84, 0x8800, v84
	ds_read2_b64 v[84:87], v84 offset1:1
	s_waitcnt lgkmcnt(0)
	v_mfma_f32_32x32x16_bf16 v[48:63], v[84:87], v[80:83], v[48:63]
	v_add_u32_e32 v84, v88, v94
	v_lshl_add_u32 v84, v84, 1, 0
	v_add_u32_e32 v84, 0x8800, v84
	ds_read2_b64 v[84:87], v84 offset1:1
	s_waitcnt lgkmcnt(0)
	v_mfma_f32_32x32x16_bf16 v[64:79], v[84:87], v[80:83], v[64:79]
	ds_read_b128 v[80:83], v15 offset:52320
	ds_read2_b64 v[84:87], v14 offset1:1
	v_add_u32_e32 v14, v0, v92
	v_lshl_add_u32 v14, v14, 1, 0
	v_add_u32_e32 v14, 0x8800, v14
	s_waitcnt lgkmcnt(0)
	v_mfma_f32_32x32x16_bf16 v[16:31], v[84:87], v[80:83], v[16:31]
	ds_read2_b64 v[84:87], v14 offset1:1
	v_add_u32_e32 v14, v0, v93
	v_lshl_add_u32 v14, v14, 1, 0
	v_add_u32_e32 v14, 0x8800, v14
	v_add_u32_e32 v0, v0, v94
	v_lshl_add_u32 v0, v0, 1, 0
	v_add_u32_e32 v0, 0x8800, v0
	s_waitcnt lgkmcnt(0)
	v_mfma_f32_32x32x16_bf16 v[32:47], v[84:87], v[80:83], v[32:47]
	ds_read2_b64 v[84:87], v14 offset1:1
	v_mov_b32_e32 v14, v208
	s_waitcnt lgkmcnt(0)
	v_mfma_f32_32x32x16_bf16 v[48:63], v[84:87], v[80:83], v[48:63]
	ds_read2_b64 v[84:87], v0 offset1:1
	v_mov_b32_e32 v0, v236
	s_waitcnt lgkmcnt(0)
	v_ashrrev_i32_e32 v15, 4, v0
	s_barrier
	v_mfma_f32_32x32x16_bf16 v[64:79], v[84:87], v[80:83], v[64:79]
	v_lshlrev_b32_e32 v82, 3, v0
	v_and_b32_e32 v80, 0x78, v82
	v_mad_u64_u32 v[80:81], s[0:1], v15, s31, v[80:81]
	v_lshl_add_u32 v15, v80, 1, 0
	ds_write_b128 v15, v[164:167]
	ds_write_b128 v15, v[168:171] offset:8704
	v_ashrrev_i32_e32 v15, 3, v0
	v_and_b32_e32 v80, 56, v82
	v_mad_u64_u32 v[82:83], s[0:1], v15, s63, v[80:81]
	v_lshl_add_u32 v81, v82, 1, 0
	v_lshl_add_u32 v15, v15, 2, v82
	v_add_u32_e32 v83, 0x8800, v81
	v_lshl_add_u32 v15, v15, 1, 0
	v_add_u32_e32 v81, 0xaa00, v81
	ds_write2_b64 v83, v[172:173], v[174:175] offset1:1
	ds_write2_b64 v81, v[176:177], v[178:179] offset1:1
	ds_write_b128 v15, v[180:183] offset:52224
	v_add_u32_e32 v15, 0x200, v0
	v_lshrrev_b32_e32 v15, 3, v15
	v_mad_u64_u32 v[82:83], s[0:1], v15, s53, v[80:81]
	v_lshl_add_u32 v15, v82, 1, 0
	ds_write_b128 v15, v[184:187] offset:52224
	v_add_u32_e32 v15, 0x400, v0
	v_lshrrev_b32_e32 v15, 3, v15
	v_mad_u64_u32 v[82:83], s[0:1], v15, s53, v[80:81]
	v_lshl_add_u32 v15, v82, 1, 0
	ds_write_b128 v15, v[188:191] offset:52224
	v_add_u32_e32 v15, 0x600, v0
	v_lshrrev_b32_e32 v15, 3, v15
	v_mad_u64_u32 v[80:81], s[0:1], v15, s53, v[80:81]
	v_lshl_add_u32 v15, v80, 1, 0
	v_cmp_gt_i32_e32 vcc, s60, v0
	ds_write_b128 v15, v[192:195] offset:52224
	s_and_saveexec_b64 s[38:39], vcc
	v_lshl_add_u32 v0, v0, 2, 0
	v_add_u32_e32 v0, 0x17400, v0
	ds_write_b32 v0, v213
	s_or_b64 exec, exec, s[38:39]
	s_cmp_ge_u32 s79, s43
	s_waitcnt lgkmcnt(0)
	s_barrier
	s_cbranch_scc1 .LBB0_493
	s_and_b64 s[0:1], s[34:35], exec
	s_cselect_b32 s0, s79, s78
	s_lshl_b32 s0, s0, 6
	s_add_i32 s0, s0, s44
	s_ashr_i32 s1, s0, 4
	s_or_b32 s1, s1, s11
	s_lshl_b32 s1, s1, 1
	s_or_b32 s38, s1, s42
	s_ashr_i32 s39, s38, 31
	s_lshl_b64 s[4:5], s[38:39], 14
	s_add_u32 s6, s92, s4
	s_addc_u32 s7, s93, s5
	s_add_u32 s4, s73, s4
	v_mov_b32_e32 v80, v236
	s_addc_u32 s5, s74, s5
	s_ashr_i32 s1, s0, 31
	v_lshlrev_b32_e32 v0, 3, v80
	v_lshlrev_b64 v[82:83], 1, v[0:1]
	v_add_u32_e32 v86, 0x1000, v0
	v_mov_b32_e32 v87, v1
	s_lshl_b64 s[0:1], s[0:1], 1
	v_lshl_add_u64 v[84:85], s[6:7], 0, v[82:83]
	v_lshlrev_b64 v[86:87], 1, v[86:87]
	s_add_u32 s0, s45, s0
	v_lshlrev_b32_e32 v15, 11, v80
	v_and_b32_e32 v0, 56, v0
	v_lshl_add_u64 v[88:89], s[6:7], 0, v[86:87]
	flat_load_dwordx4 v[164:167], v[84:85]
	flat_load_dwordx4 v[168:171], v[88:89]
	v_lshl_add_u64 v[82:83], s[4:5], 0, v[82:83]
	v_lshl_add_u64 v[84:85], s[4:5], 0, v[86:87]
	s_addc_u32 s1, s70, s1
	v_and_or_b32 v0, v15, s62, v0
	flat_load_dwordx4 v[172:175], v[82:83]
	flat_load_dwordx4 v[176:179], v[84:85]
	v_lshl_add_u64 v[82:83], v[0:1], 1, s[0:1]
	v_add_u32_e32 v84, 0x100000, v0
	v_mov_b32_e32 v85, v1
	v_lshl_add_u64 v[84:85], v[84:85], 1, s[0:1]
	flat_load_dwordx4 v[180:183], v[82:83]
	flat_load_dwordx4 v[184:187], v[84:85]
	v_add_u32_e32 v82, 0x200000, v0
	v_mov_b32_e32 v83, v1
	v_lshl_add_u64 v[82:83], v[82:83], 1, s[0:1]
	v_add_u32_e32 v0, 0x300000, v0
	v_lshl_add_u64 v[84:85], v[0:1], 1, s[0:1]
	flat_load_dwordx4 v[188:191], v[82:83]
	flat_load_dwordx4 v[192:195], v[84:85]
	v_cmp_gt_i32_e32 vcc, s60, v80
	s_and_saveexec_b64 s[40:41], vcc
	s_cbranch_execz .LBB0_492
	s_lshl_b64 s[0:1], s[38:39], 9
	s_add_u32 s0, s75, s0
	s_addc_u32 s1, s86, s1
	v_mov_b32_e32 v81, v1
	v_lshl_add_u64 v[80:81], v[80:81], 2, s[0:1]
	flat_load_dword v213, v[80:81]
	s_branch .LBB0_492
